# hand-written software-pipelined merge epilogue (gate loads 6 chunks deep for rescale segments, 10 deep for final gated store) replacing compiler's load-wait-load-wait chain
# baseline (speedup 1.0000x reference)
.LBB0_925:
	v_lshl_add_u32 v161, s42, 8, v150
	v_lshl_or_b32 v162, s35, 8, v159
	v_readlane_b32 s34, v251, 14
	v_readlane_b32 s35, v251, 15
	v_readlane_b32 s16, v253, 51
	v_readlane_b32 s17, v253, 52
	v_mul_u32_u24_e32 v142, s78, v161
	v_lshl_add_u32 v142, v162, 1, v142
	v_lshlrev_b32_e32 v143, 12, v161
	v_lshl_add_u32 v143, v162, 1, v143
	s_cmp_gt_i32 s47, 1
	s_cbranch_scc1 .Lmg_fin
	s_lshl_b32 s2, s47, 12
	s_add_i32 s2, s2, 0x4a00
	v_add_u32_e32 v142, s2, v142
	global_load_dwordx4 v[164:167], v142, s[34:35] offset:-4096
	global_load_dwordx4 v[168:171], v142, s[34:35]
	global_load_dwordx4 v[172:175], v142, s[34:35] offset:-3840
	global_load_dwordx4 v[176:179], v142, s[34:35] offset:256
	v_add_u32_e32 v142, 0x6a000, v142
	global_load_dwordx4 v[180:183], v142, s[34:35] offset:-4096
	global_load_dwordx4 v[184:187], v142, s[34:35]
	global_load_dwordx4 v[188:191], v142, s[34:35] offset:-3840
	global_load_dwordx4 v[192:195], v142, s[34:35] offset:256
	v_add_u32_e32 v142, 0x6a000, v142
	global_load_dwordx4 v[196:199], v142, s[34:35] offset:-4096
	global_load_dwordx4 v[224:227], v142, s[34:35]
	global_load_dwordx4 v[228:231], v142, s[34:35] offset:-3840
	global_load_dwordx4 v[232:235], v142, s[34:35] offset:256
	v_add_u32_e32 v142, 0x6a000, v142
	s_waitcnt vmcnt(10)
	v_lshlrev_b32_e32 v236, 16, v168
	v_and_b32_e32 v237, 0xffff0000, v168
	v_lshlrev_b32_e32 v238, 16, v169
	v_and_b32_e32 v239, 0xffff0000, v169
	v_lshlrev_b32_e32 v240, 16, v170
	v_and_b32_e32 v241, 0xffff0000, v170
	v_lshlrev_b32_e32 v242, 16, v171
	v_and_b32_e32 v243, 0xffff0000, v171
	v_max_f32_e32 v236, 0xda24260, v236
	v_max_f32_e32 v237, 0xda24260, v237
	v_max_f32_e32 v238, 0xda24260, v238
	v_max_f32_e32 v239, 0xda24260, v239
	v_max_f32_e32 v240, 0xda24260, v240
	v_max_f32_e32 v241, 0xda24260, v241
	v_max_f32_e32 v242, 0xda24260, v242
	v_max_f32_e32 v243, 0xda24260, v243
	v_rcp_f32_e32 v236, v236
	v_rcp_f32_e32 v237, v237
	v_rcp_f32_e32 v238, v238
	v_rcp_f32_e32 v239, v239
	v_rcp_f32_e32 v240, v240
	v_rcp_f32_e32 v241, v241
	v_rcp_f32_e32 v242, v242
	v_rcp_f32_e32 v243, v243
	v_lshlrev_b32_e32 v244, 16, v164
	v_and_b32_e32 v245, 0xffff0000, v164
	v_lshlrev_b32_e32 v246, 16, v165
	v_and_b32_e32 v247, 0xffff0000, v165
	v_lshlrev_b32_e32 v248, 16, v166
	v_and_b32_e32 v249, 0xffff0000, v166
	v_lshlrev_b32_e32 v140, 16, v167
	v_and_b32_e32 v141, 0xffff0000, v167
	v_pk_mul_f32 v[236:237], v[236:237], v[244:245]
	v_pk_mul_f32 v[238:239], v[238:239], v[246:247]
	v_pk_mul_f32 v[240:241], v[240:241], v[248:249]
	v_pk_mul_f32 v[242:243], v[242:243], v[140:141]
	v_pk_mul_f32 v[126:127], v[126:127], v[236:237]
	v_pk_mul_f32 v[128:129], v[128:129], v[238:239]
	v_pk_mul_f32 v[122:123], v[122:123], v[240:241]
	v_pk_mul_f32 v[124:125], v[124:125], v[242:243]
	global_load_dwordx4 v[164:167], v142, s[34:35] offset:-4096
	global_load_dwordx4 v[168:171], v142, s[34:35]
	s_waitcnt vmcnt(10)
	v_lshlrev_b32_e32 v236, 16, v176
	v_and_b32_e32 v237, 0xffff0000, v176
	v_lshlrev_b32_e32 v238, 16, v177
	v_and_b32_e32 v239, 0xffff0000, v177
	v_lshlrev_b32_e32 v240, 16, v178
	v_and_b32_e32 v241, 0xffff0000, v178
	v_lshlrev_b32_e32 v242, 16, v179
	v_and_b32_e32 v243, 0xffff0000, v179
	v_max_f32_e32 v236, 0xda24260, v236
	v_max_f32_e32 v237, 0xda24260, v237
	v_max_f32_e32 v238, 0xda24260, v238
	v_max_f32_e32 v239, 0xda24260, v239
	v_max_f32_e32 v240, 0xda24260, v240
	v_max_f32_e32 v241, 0xda24260, v241
	v_max_f32_e32 v242, 0xda24260, v242
	v_max_f32_e32 v243, 0xda24260, v243
	v_rcp_f32_e32 v236, v236
	v_rcp_f32_e32 v237, v237
	v_rcp_f32_e32 v238, v238
	v_rcp_f32_e32 v239, v239
	v_rcp_f32_e32 v240, v240
	v_rcp_f32_e32 v241, v241
	v_rcp_f32_e32 v242, v242
	v_rcp_f32_e32 v243, v243
	v_lshlrev_b32_e32 v244, 16, v172
	v_and_b32_e32 v245, 0xffff0000, v172
	v_lshlrev_b32_e32 v246, 16, v173
	v_and_b32_e32 v247, 0xffff0000, v173
	v_lshlrev_b32_e32 v248, 16, v174
	v_and_b32_e32 v249, 0xffff0000, v174
	v_lshlrev_b32_e32 v140, 16, v175
	v_and_b32_e32 v141, 0xffff0000, v175
	v_pk_mul_f32 v[236:237], v[236:237], v[244:245]
	v_pk_mul_f32 v[238:239], v[238:239], v[246:247]
	v_pk_mul_f32 v[240:241], v[240:241], v[248:249]
	v_pk_mul_f32 v[242:243], v[242:243], v[140:141]
	v_pk_mul_f32 v[94:95], v[94:95], v[236:237]
	v_pk_mul_f32 v[96:97], v[96:97], v[238:239]
	v_pk_mul_f32 v[90:91], v[90:91], v[240:241]
	v_pk_mul_f32 v[92:93], v[92:93], v[242:243]
	global_load_dwordx4 v[172:175], v142, s[34:35] offset:-3840
	global_load_dwordx4 v[176:179], v142, s[34:35] offset:256
	v_add_u32_e32 v142, 0x212000, v142
	s_waitcnt vmcnt(10)
	v_lshlrev_b32_e32 v236, 16, v184
	v_and_b32_e32 v237, 0xffff0000, v184
	v_lshlrev_b32_e32 v238, 16, v185
	v_and_b32_e32 v239, 0xffff0000, v185
	v_lshlrev_b32_e32 v240, 16, v186
	v_and_b32_e32 v241, 0xffff0000, v186
	v_lshlrev_b32_e32 v242, 16, v187
	v_and_b32_e32 v243, 0xffff0000, v187
	v_max_f32_e32 v236, 0xda24260, v236
	v_max_f32_e32 v237, 0xda24260, v237
	v_max_f32_e32 v238, 0xda24260, v238
	v_max_f32_e32 v239, 0xda24260, v239
	v_max_f32_e32 v240, 0xda24260, v240
	v_max_f32_e32 v241, 0xda24260, v241
	v_max_f32_e32 v242, 0xda24260, v242
	v_max_f32_e32 v243, 0xda24260, v243
	v_rcp_f32_e32 v236, v236
	v_rcp_f32_e32 v237, v237
	v_rcp_f32_e32 v238, v238
	v_rcp_f32_e32 v239, v239
	v_rcp_f32_e32 v240, v240
	v_rcp_f32_e32 v241, v241
	v_rcp_f32_e32 v242, v242
	v_rcp_f32_e32 v243, v243
	v_lshlrev_b32_e32 v244, 16, v180
	v_and_b32_e32 v245, 0xffff0000, v180
	v_lshlrev_b32_e32 v246, 16, v181
	v_and_b32_e32 v247, 0xffff0000, v181
	v_lshlrev_b32_e32 v248, 16, v182
	v_and_b32_e32 v249, 0xffff0000, v182
	v_lshlrev_b32_e32 v140, 16, v183
	v_and_b32_e32 v141, 0xffff0000, v183
	v_pk_mul_f32 v[236:237], v[236:237], v[244:245]
	v_pk_mul_f32 v[238:239], v[238:239], v[246:247]
	v_pk_mul_f32 v[240:241], v[240:241], v[248:249]
	v_pk_mul_f32 v[242:243], v[242:243], v[140:141]
	v_pk_mul_f32 v[118:119], v[118:119], v[236:237]
	v_pk_mul_f32 v[120:121], v[120:121], v[238:239]
	v_pk_mul_f32 v[114:115], v[114:115], v[240:241]
	v_pk_mul_f32 v[116:117], v[116:117], v[242:243]
	global_load_dwordx4 v[180:183], v142, s[34:35] offset:-4096
	global_load_dwordx4 v[184:187], v142, s[34:35]
	s_waitcnt vmcnt(10)
	v_lshlrev_b32_e32 v236, 16, v192
	v_and_b32_e32 v237, 0xffff0000, v192
	v_lshlrev_b32_e32 v238, 16, v193
	v_and_b32_e32 v239, 0xffff0000, v193
	v_lshlrev_b32_e32 v240, 16, v194
	v_and_b32_e32 v241, 0xffff0000, v194
	v_lshlrev_b32_e32 v242, 16, v195
	v_and_b32_e32 v243, 0xffff0000, v195
	v_max_f32_e32 v236, 0xda24260, v236
	v_max_f32_e32 v237, 0xda24260, v237
	v_max_f32_e32 v238, 0xda24260, v238
	v_max_f32_e32 v239, 0xda24260, v239
	v_max_f32_e32 v240, 0xda24260, v240
	v_max_f32_e32 v241, 0xda24260, v241
	v_max_f32_e32 v242, 0xda24260, v242
	v_max_f32_e32 v243, 0xda24260, v243
	v_rcp_f32_e32 v236, v236
	v_rcp_f32_e32 v237, v237
	v_rcp_f32_e32 v238, v238
	v_rcp_f32_e32 v239, v239
	v_rcp_f32_e32 v240, v240
	v_rcp_f32_e32 v241, v241
	v_rcp_f32_e32 v242, v242
	v_rcp_f32_e32 v243, v243
	v_lshlrev_b32_e32 v244, 16, v188
	v_and_b32_e32 v245, 0xffff0000, v188
	v_lshlrev_b32_e32 v246, 16, v189
	v_and_b32_e32 v247, 0xffff0000, v189
	v_lshlrev_b32_e32 v248, 16, v190
	v_and_b32_e32 v249, 0xffff0000, v190
	v_lshlrev_b32_e32 v140, 16, v191
	v_and_b32_e32 v141, 0xffff0000, v191
	v_pk_mul_f32 v[236:237], v[236:237], v[244:245]
	v_pk_mul_f32 v[238:239], v[238:239], v[246:247]
	v_pk_mul_f32 v[240:241], v[240:241], v[248:249]
	v_pk_mul_f32 v[242:243], v[242:243], v[140:141]
	v_pk_mul_f32 v[86:87], v[86:87], v[236:237]
	v_pk_mul_f32 v[88:89], v[88:89], v[238:239]
	v_pk_mul_f32 v[82:83], v[82:83], v[240:241]
	v_pk_mul_f32 v[84:85], v[84:85], v[242:243]
	global_load_dwordx4 v[188:191], v142, s[34:35] offset:-3840
	global_load_dwordx4 v[192:195], v142, s[34:35] offset:256
	v_add_u32_e32 v142, 0x6a000, v142
	s_waitcnt vmcnt(10)
	v_lshlrev_b32_e32 v236, 16, v224
	v_and_b32_e32 v237, 0xffff0000, v224
	v_lshlrev_b32_e32 v238, 16, v225
	v_and_b32_e32 v239, 0xffff0000, v225
	v_lshlrev_b32_e32 v240, 16, v226
	v_and_b32_e32 v241, 0xffff0000, v226
	v_lshlrev_b32_e32 v242, 16, v227
	v_and_b32_e32 v243, 0xffff0000, v227
	v_max_f32_e32 v236, 0xda24260, v236
	v_max_f32_e32 v237, 0xda24260, v237
	v_max_f32_e32 v238, 0xda24260, v238
	v_max_f32_e32 v239, 0xda24260, v239
	v_max_f32_e32 v240, 0xda24260, v240
	v_max_f32_e32 v241, 0xda24260, v241
	v_max_f32_e32 v242, 0xda24260, v242
	v_max_f32_e32 v243, 0xda24260, v243
	v_rcp_f32_e32 v236, v236
	v_rcp_f32_e32 v237, v237
	v_rcp_f32_e32 v238, v238
	v_rcp_f32_e32 v239, v239
	v_rcp_f32_e32 v240, v240
	v_rcp_f32_e32 v241, v241
	v_rcp_f32_e32 v242, v242
	v_rcp_f32_e32 v243, v243
	v_lshlrev_b32_e32 v244, 16, v196
	v_and_b32_e32 v245, 0xffff0000, v196
	v_lshlrev_b32_e32 v246, 16, v197
	v_and_b32_e32 v247, 0xffff0000, v197
	v_lshlrev_b32_e32 v248, 16, v198
	v_and_b32_e32 v249, 0xffff0000, v198
	v_lshlrev_b32_e32 v140, 16, v199
	v_and_b32_e32 v141, 0xffff0000, v199
	v_pk_mul_f32 v[236:237], v[236:237], v[244:245]
	v_pk_mul_f32 v[238:239], v[238:239], v[246:247]
	v_pk_mul_f32 v[240:241], v[240:241], v[248:249]
	v_pk_mul_f32 v[242:243], v[242:243], v[140:141]
	v_pk_mul_f32 v[110:111], v[110:111], v[236:237]
	v_pk_mul_f32 v[112:113], v[112:113], v[238:239]
	v_pk_mul_f32 v[106:107], v[106:107], v[240:241]
	v_pk_mul_f32 v[108:109], v[108:109], v[242:243]
	global_load_dwordx4 v[196:199], v142, s[34:35] offset:-4096
	global_load_dwordx4 v[224:227], v142, s[34:35]
	s_waitcnt vmcnt(10)
	v_lshlrev_b32_e32 v236, 16, v232
	v_and_b32_e32 v237, 0xffff0000, v232
	v_lshlrev_b32_e32 v238, 16, v233
	v_and_b32_e32 v239, 0xffff0000, v233
	v_lshlrev_b32_e32 v240, 16, v234
	v_and_b32_e32 v241, 0xffff0000, v234
	v_lshlrev_b32_e32 v242, 16, v235
	v_and_b32_e32 v243, 0xffff0000, v235
	v_max_f32_e32 v236, 0xda24260, v236
	v_max_f32_e32 v237, 0xda24260, v237
	v_max_f32_e32 v238, 0xda24260, v238
	v_max_f32_e32 v239, 0xda24260, v239
	v_max_f32_e32 v240, 0xda24260, v240
	v_max_f32_e32 v241, 0xda24260, v241
	v_max_f32_e32 v242, 0xda24260, v242
	v_max_f32_e32 v243, 0xda24260, v243
	v_rcp_f32_e32 v236, v236
	v_rcp_f32_e32 v237, v237
	v_rcp_f32_e32 v238, v238
	v_rcp_f32_e32 v239, v239
	v_rcp_f32_e32 v240, v240
	v_rcp_f32_e32 v241, v241
	v_rcp_f32_e32 v242, v242
	v_rcp_f32_e32 v243, v243
	v_lshlrev_b32_e32 v244, 16, v228
	v_and_b32_e32 v245, 0xffff0000, v228
	v_lshlrev_b32_e32 v246, 16, v229
	v_and_b32_e32 v247, 0xffff0000, v229
	v_lshlrev_b32_e32 v248, 16, v230
	v_and_b32_e32 v249, 0xffff0000, v230
	v_lshlrev_b32_e32 v140, 16, v231
	v_and_b32_e32 v141, 0xffff0000, v231
	v_pk_mul_f32 v[236:237], v[236:237], v[244:245]
	v_pk_mul_f32 v[238:239], v[238:239], v[246:247]
	v_pk_mul_f32 v[240:241], v[240:241], v[248:249]
	v_pk_mul_f32 v[242:243], v[242:243], v[140:141]
	v_pk_mul_f32 v[78:79], v[78:79], v[236:237]
	v_pk_mul_f32 v[80:81], v[80:81], v[238:239]
	v_pk_mul_f32 v[74:75], v[74:75], v[240:241]
	v_pk_mul_f32 v[76:77], v[76:77], v[242:243]
	global_load_dwordx4 v[228:231], v142, s[34:35] offset:-3840
	global_load_dwordx4 v[232:235], v142, s[34:35] offset:256
	v_add_u32_e32 v142, 0x6a000, v142
	s_waitcnt vmcnt(10)
	v_lshlrev_b32_e32 v236, 16, v168
	v_and_b32_e32 v237, 0xffff0000, v168
	v_lshlrev_b32_e32 v238, 16, v169
	v_and_b32_e32 v239, 0xffff0000, v169
	v_lshlrev_b32_e32 v240, 16, v170
	v_and_b32_e32 v241, 0xffff0000, v170
	v_lshlrev_b32_e32 v242, 16, v171
	v_and_b32_e32 v243, 0xffff0000, v171
	v_max_f32_e32 v236, 0xda24260, v236
	v_max_f32_e32 v237, 0xda24260, v237
	v_max_f32_e32 v238, 0xda24260, v238
	v_max_f32_e32 v239, 0xda24260, v239
	v_max_f32_e32 v240, 0xda24260, v240
	v_max_f32_e32 v241, 0xda24260, v241
	v_max_f32_e32 v242, 0xda24260, v242
	v_max_f32_e32 v243, 0xda24260, v243
	v_rcp_f32_e32 v236, v236
	v_rcp_f32_e32 v237, v237
	v_rcp_f32_e32 v238, v238
	v_rcp_f32_e32 v239, v239
	v_rcp_f32_e32 v240, v240
	v_rcp_f32_e32 v241, v241
	v_rcp_f32_e32 v242, v242
	v_rcp_f32_e32 v243, v243
	v_lshlrev_b32_e32 v244, 16, v164
	v_and_b32_e32 v245, 0xffff0000, v164
	v_lshlrev_b32_e32 v246, 16, v165
	v_and_b32_e32 v247, 0xffff0000, v165
	v_lshlrev_b32_e32 v248, 16, v166
	v_and_b32_e32 v249, 0xffff0000, v166
	v_lshlrev_b32_e32 v140, 16, v167
	v_and_b32_e32 v141, 0xffff0000, v167
	v_pk_mul_f32 v[236:237], v[236:237], v[244:245]
	v_pk_mul_f32 v[238:239], v[238:239], v[246:247]
	v_pk_mul_f32 v[240:241], v[240:241], v[248:249]
	v_pk_mul_f32 v[242:243], v[242:243], v[140:141]
	v_pk_mul_f32 v[102:103], v[102:103], v[236:237]
	v_pk_mul_f32 v[104:105], v[104:105], v[238:239]
	v_pk_mul_f32 v[98:99], v[98:99], v[240:241]
	v_pk_mul_f32 v[100:101], v[100:101], v[242:243]
	global_load_dwordx4 v[164:167], v142, s[34:35] offset:-4096
	global_load_dwordx4 v[168:171], v142, s[34:35]
	s_waitcnt vmcnt(10)
	v_lshlrev_b32_e32 v236, 16, v176
	v_and_b32_e32 v237, 0xffff0000, v176
	v_lshlrev_b32_e32 v238, 16, v177
	v_and_b32_e32 v239, 0xffff0000, v177
	v_lshlrev_b32_e32 v240, 16, v178
	v_and_b32_e32 v241, 0xffff0000, v178
	v_lshlrev_b32_e32 v242, 16, v179
	v_and_b32_e32 v243, 0xffff0000, v179
	v_max_f32_e32 v236, 0xda24260, v236
	v_max_f32_e32 v237, 0xda24260, v237
	v_max_f32_e32 v238, 0xda24260, v238
	v_max_f32_e32 v239, 0xda24260, v239
	v_max_f32_e32 v240, 0xda24260, v240
	v_max_f32_e32 v241, 0xda24260, v241
	v_max_f32_e32 v242, 0xda24260, v242
	v_max_f32_e32 v243, 0xda24260, v243
	v_rcp_f32_e32 v236, v236
	v_rcp_f32_e32 v237, v237
	v_rcp_f32_e32 v238, v238
	v_rcp_f32_e32 v239, v239
	v_rcp_f32_e32 v240, v240
	v_rcp_f32_e32 v241, v241
	v_rcp_f32_e32 v242, v242
	v_rcp_f32_e32 v243, v243
	v_lshlrev_b32_e32 v244, 16, v172
	v_and_b32_e32 v245, 0xffff0000, v172
	v_lshlrev_b32_e32 v246, 16, v173
	v_and_b32_e32 v247, 0xffff0000, v173
	v_lshlrev_b32_e32 v248, 16, v174
	v_and_b32_e32 v249, 0xffff0000, v174
	v_lshlrev_b32_e32 v140, 16, v175
	v_and_b32_e32 v141, 0xffff0000, v175
	v_pk_mul_f32 v[236:237], v[236:237], v[244:245]
	v_pk_mul_f32 v[238:239], v[238:239], v[246:247]
	v_pk_mul_f32 v[240:241], v[240:241], v[248:249]
	v_pk_mul_f32 v[242:243], v[242:243], v[140:141]
	v_pk_mul_f32 v[70:71], v[70:71], v[236:237]
	v_pk_mul_f32 v[72:73], v[72:73], v[238:239]
	v_pk_mul_f32 v[66:67], v[66:67], v[240:241]
	v_pk_mul_f32 v[68:69], v[68:69], v[242:243]
	global_load_dwordx4 v[172:175], v142, s[34:35] offset:-3840
	global_load_dwordx4 v[176:179], v142, s[34:35] offset:256
	v_add_u32_e32 v142, 0x6a000, v142
	s_waitcnt vmcnt(10)
	v_lshlrev_b32_e32 v236, 16, v184
	v_and_b32_e32 v237, 0xffff0000, v184
	v_lshlrev_b32_e32 v238, 16, v185
	v_and_b32_e32 v239, 0xffff0000, v185
	v_lshlrev_b32_e32 v240, 16, v186
	v_and_b32_e32 v241, 0xffff0000, v186
	v_lshlrev_b32_e32 v242, 16, v187
	v_and_b32_e32 v243, 0xffff0000, v187
	v_max_f32_e32 v236, 0xda24260, v236
	v_max_f32_e32 v237, 0xda24260, v237
	v_max_f32_e32 v238, 0xda24260, v238
	v_max_f32_e32 v239, 0xda24260, v239
	v_max_f32_e32 v240, 0xda24260, v240
	v_max_f32_e32 v241, 0xda24260, v241
	v_max_f32_e32 v242, 0xda24260, v242
	v_max_f32_e32 v243, 0xda24260, v243
	v_rcp_f32_e32 v236, v236
	v_rcp_f32_e32 v237, v237
	v_rcp_f32_e32 v238, v238
	v_rcp_f32_e32 v239, v239
	v_rcp_f32_e32 v240, v240
	v_rcp_f32_e32 v241, v241
	v_rcp_f32_e32 v242, v242
	v_rcp_f32_e32 v243, v243
	v_lshlrev_b32_e32 v244, 16, v180
	v_and_b32_e32 v245, 0xffff0000, v180
	v_lshlrev_b32_e32 v246, 16, v181
	v_and_b32_e32 v247, 0xffff0000, v181
	v_lshlrev_b32_e32 v248, 16, v182
	v_and_b32_e32 v249, 0xffff0000, v182
	v_lshlrev_b32_e32 v140, 16, v183
	v_and_b32_e32 v141, 0xffff0000, v183
	v_pk_mul_f32 v[236:237], v[236:237], v[244:245]
	v_pk_mul_f32 v[238:239], v[238:239], v[246:247]
	v_pk_mul_f32 v[240:241], v[240:241], v[248:249]
	v_pk_mul_f32 v[242:243], v[242:243], v[140:141]
	v_pk_mul_f32 v[62:63], v[62:63], v[236:237]
	v_pk_mul_f32 v[64:65], v[64:65], v[238:239]
	v_pk_mul_f32 v[58:59], v[58:59], v[240:241]
	v_pk_mul_f32 v[60:61], v[60:61], v[242:243]
	global_load_dwordx4 v[180:183], v142, s[34:35] offset:-4096
	global_load_dwordx4 v[184:187], v142, s[34:35]
	s_waitcnt vmcnt(10)
	v_lshlrev_b32_e32 v236, 16, v192
	v_and_b32_e32 v237, 0xffff0000, v192
	v_lshlrev_b32_e32 v238, 16, v193
	v_and_b32_e32 v239, 0xffff0000, v193
	v_lshlrev_b32_e32 v240, 16, v194
	v_and_b32_e32 v241, 0xffff0000, v194
	v_lshlrev_b32_e32 v242, 16, v195
	v_and_b32_e32 v243, 0xffff0000, v195
	v_max_f32_e32 v236, 0xda24260, v236
	v_max_f32_e32 v237, 0xda24260, v237
	v_max_f32_e32 v238, 0xda24260, v238
	v_max_f32_e32 v239, 0xda24260, v239
	v_max_f32_e32 v240, 0xda24260, v240
	v_max_f32_e32 v241, 0xda24260, v241
	v_max_f32_e32 v242, 0xda24260, v242
	v_max_f32_e32 v243, 0xda24260, v243
	v_rcp_f32_e32 v236, v236
	v_rcp_f32_e32 v237, v237
	v_rcp_f32_e32 v238, v238
	v_rcp_f32_e32 v239, v239
	v_rcp_f32_e32 v240, v240
	v_rcp_f32_e32 v241, v241
	v_rcp_f32_e32 v242, v242
	v_rcp_f32_e32 v243, v243
	v_lshlrev_b32_e32 v244, 16, v188
	v_and_b32_e32 v245, 0xffff0000, v188
	v_lshlrev_b32_e32 v246, 16, v189
	v_and_b32_e32 v247, 0xffff0000, v189
	v_lshlrev_b32_e32 v248, 16, v190
	v_and_b32_e32 v249, 0xffff0000, v190
	v_lshlrev_b32_e32 v140, 16, v191
	v_and_b32_e32 v141, 0xffff0000, v191
	v_pk_mul_f32 v[236:237], v[236:237], v[244:245]
	v_pk_mul_f32 v[238:239], v[238:239], v[246:247]
	v_pk_mul_f32 v[240:241], v[240:241], v[248:249]
	v_pk_mul_f32 v[242:243], v[242:243], v[140:141]
	v_pk_mul_f32 v[30:31], v[30:31], v[236:237]
	v_pk_mul_f32 v[32:33], v[32:33], v[238:239]
	v_pk_mul_f32 v[26:27], v[26:27], v[240:241]
	v_pk_mul_f32 v[28:29], v[28:29], v[242:243]
	global_load_dwordx4 v[188:191], v142, s[34:35] offset:-3840
	global_load_dwordx4 v[192:195], v142, s[34:35] offset:256
	s_waitcnt vmcnt(10)
	v_lshlrev_b32_e32 v236, 16, v224
	v_and_b32_e32 v237, 0xffff0000, v224
	v_lshlrev_b32_e32 v238, 16, v225
	v_and_b32_e32 v239, 0xffff0000, v225
	v_lshlrev_b32_e32 v240, 16, v226
	v_and_b32_e32 v241, 0xffff0000, v226
	v_lshlrev_b32_e32 v242, 16, v227
	v_and_b32_e32 v243, 0xffff0000, v227
	v_max_f32_e32 v236, 0xda24260, v236
	v_max_f32_e32 v237, 0xda24260, v237
	v_max_f32_e32 v238, 0xda24260, v238
	v_max_f32_e32 v239, 0xda24260, v239
	v_max_f32_e32 v240, 0xda24260, v240
	v_max_f32_e32 v241, 0xda24260, v241
	v_max_f32_e32 v242, 0xda24260, v242
	v_max_f32_e32 v243, 0xda24260, v243
	v_rcp_f32_e32 v236, v236
	v_rcp_f32_e32 v237, v237
	v_rcp_f32_e32 v238, v238
	v_rcp_f32_e32 v239, v239
	v_rcp_f32_e32 v240, v240
	v_rcp_f32_e32 v241, v241
	v_rcp_f32_e32 v242, v242
	v_rcp_f32_e32 v243, v243
	v_lshlrev_b32_e32 v244, 16, v196
	v_and_b32_e32 v245, 0xffff0000, v196
	v_lshlrev_b32_e32 v246, 16, v197
	v_and_b32_e32 v247, 0xffff0000, v197
	v_lshlrev_b32_e32 v248, 16, v198
	v_and_b32_e32 v249, 0xffff0000, v198
	v_lshlrev_b32_e32 v140, 16, v199
	v_and_b32_e32 v141, 0xffff0000, v199
	v_pk_mul_f32 v[236:237], v[236:237], v[244:245]
	v_pk_mul_f32 v[238:239], v[238:239], v[246:247]
	v_pk_mul_f32 v[240:241], v[240:241], v[248:249]
	v_pk_mul_f32 v[242:243], v[242:243], v[140:141]
	v_pk_mul_f32 v[54:55], v[54:55], v[236:237]
	v_pk_mul_f32 v[56:57], v[56:57], v[238:239]
	v_pk_mul_f32 v[50:51], v[50:51], v[240:241]
	v_pk_mul_f32 v[52:53], v[52:53], v[242:243]
	s_waitcnt vmcnt(8)
	v_lshlrev_b32_e32 v236, 16, v232
	v_and_b32_e32 v237, 0xffff0000, v232
	v_lshlrev_b32_e32 v238, 16, v233
	v_and_b32_e32 v239, 0xffff0000, v233
	v_lshlrev_b32_e32 v240, 16, v234
	v_and_b32_e32 v241, 0xffff0000, v234
	v_lshlrev_b32_e32 v242, 16, v235
	v_and_b32_e32 v243, 0xffff0000, v235
	v_max_f32_e32 v236, 0xda24260, v236
	v_max_f32_e32 v237, 0xda24260, v237
	v_max_f32_e32 v238, 0xda24260, v238
	v_max_f32_e32 v239, 0xda24260, v239
	v_max_f32_e32 v240, 0xda24260, v240
	v_max_f32_e32 v241, 0xda24260, v241
	v_max_f32_e32 v242, 0xda24260, v242
	v_max_f32_e32 v243, 0xda24260, v243
	v_rcp_f32_e32 v236, v236
	v_rcp_f32_e32 v237, v237
	v_rcp_f32_e32 v238, v238
	v_rcp_f32_e32 v239, v239
	v_rcp_f32_e32 v240, v240
	v_rcp_f32_e32 v241, v241
	v_rcp_f32_e32 v242, v242
	v_rcp_f32_e32 v243, v243
	v_lshlrev_b32_e32 v244, 16, v228
	v_and_b32_e32 v245, 0xffff0000, v228
	v_lshlrev_b32_e32 v246, 16, v229
	v_and_b32_e32 v247, 0xffff0000, v229
	v_lshlrev_b32_e32 v248, 16, v230
	v_and_b32_e32 v249, 0xffff0000, v230
	v_lshlrev_b32_e32 v140, 16, v231
	v_and_b32_e32 v141, 0xffff0000, v231
	v_pk_mul_f32 v[236:237], v[236:237], v[244:245]
	v_pk_mul_f32 v[238:239], v[238:239], v[246:247]
	v_pk_mul_f32 v[240:241], v[240:241], v[248:249]
	v_pk_mul_f32 v[242:243], v[242:243], v[140:141]
	v_pk_mul_f32 v[22:23], v[22:23], v[236:237]
	v_pk_mul_f32 v[24:25], v[24:25], v[238:239]
	v_pk_mul_f32 v[18:19], v[18:19], v[240:241]
	v_pk_mul_f32 v[20:21], v[20:21], v[242:243]
	s_waitcnt vmcnt(6)
	v_lshlrev_b32_e32 v236, 16, v168
	v_and_b32_e32 v237, 0xffff0000, v168
	v_lshlrev_b32_e32 v238, 16, v169
	v_and_b32_e32 v239, 0xffff0000, v169
	v_lshlrev_b32_e32 v240, 16, v170
	v_and_b32_e32 v241, 0xffff0000, v170
	v_lshlrev_b32_e32 v242, 16, v171
	v_and_b32_e32 v243, 0xffff0000, v171
	v_max_f32_e32 v236, 0xda24260, v236
	v_max_f32_e32 v237, 0xda24260, v237
	v_max_f32_e32 v238, 0xda24260, v238
	v_max_f32_e32 v239, 0xda24260, v239
	v_max_f32_e32 v240, 0xda24260, v240
	v_max_f32_e32 v241, 0xda24260, v241
	v_max_f32_e32 v242, 0xda24260, v242
	v_max_f32_e32 v243, 0xda24260, v243
	v_rcp_f32_e32 v236, v236
	v_rcp_f32_e32 v237, v237
	v_rcp_f32_e32 v238, v238
	v_rcp_f32_e32 v239, v239
	v_rcp_f32_e32 v240, v240
	v_rcp_f32_e32 v241, v241
	v_rcp_f32_e32 v242, v242
	v_rcp_f32_e32 v243, v243
	v_lshlrev_b32_e32 v244, 16, v164
	v_and_b32_e32 v245, 0xffff0000, v164
	v_lshlrev_b32_e32 v246, 16, v165
	v_and_b32_e32 v247, 0xffff0000, v165
	v_lshlrev_b32_e32 v248, 16, v166
	v_and_b32_e32 v249, 0xffff0000, v166
	v_lshlrev_b32_e32 v140, 16, v167
	v_and_b32_e32 v141, 0xffff0000, v167
	v_pk_mul_f32 v[236:237], v[236:237], v[244:245]
	v_pk_mul_f32 v[238:239], v[238:239], v[246:247]
	v_pk_mul_f32 v[240:241], v[240:241], v[248:249]
	v_pk_mul_f32 v[242:243], v[242:243], v[140:141]
	v_pk_mul_f32 v[46:47], v[46:47], v[236:237]
	v_pk_mul_f32 v[48:49], v[48:49], v[238:239]
	v_pk_mul_f32 v[42:43], v[42:43], v[240:241]
	v_pk_mul_f32 v[44:45], v[44:45], v[242:243]
	s_waitcnt vmcnt(4)
	v_lshlrev_b32_e32 v236, 16, v176
	v_and_b32_e32 v237, 0xffff0000, v176
	v_lshlrev_b32_e32 v238, 16, v177
	v_and_b32_e32 v239, 0xffff0000, v177
	v_lshlrev_b32_e32 v240, 16, v178
	v_and_b32_e32 v241, 0xffff0000, v178
	v_lshlrev_b32_e32 v242, 16, v179
	v_and_b32_e32 v243, 0xffff0000, v179
	v_max_f32_e32 v236, 0xda24260, v236
	v_max_f32_e32 v237, 0xda24260, v237
	v_max_f32_e32 v238, 0xda24260, v238
	v_max_f32_e32 v239, 0xda24260, v239
	v_max_f32_e32 v240, 0xda24260, v240
	v_max_f32_e32 v241, 0xda24260, v241
	v_max_f32_e32 v242, 0xda24260, v242
	v_max_f32_e32 v243, 0xda24260, v243
	v_rcp_f32_e32 v236, v236
	v_rcp_f32_e32 v237, v237
	v_rcp_f32_e32 v238, v238
	v_rcp_f32_e32 v239, v239
	v_rcp_f32_e32 v240, v240
	v_rcp_f32_e32 v241, v241
	v_rcp_f32_e32 v242, v242
	v_rcp_f32_e32 v243, v243
	v_lshlrev_b32_e32 v244, 16, v172
	v_and_b32_e32 v245, 0xffff0000, v172
	v_lshlrev_b32_e32 v246, 16, v173
	v_and_b32_e32 v247, 0xffff0000, v173
	v_lshlrev_b32_e32 v248, 16, v174
	v_and_b32_e32 v249, 0xffff0000, v174
	v_lshlrev_b32_e32 v140, 16, v175
	v_and_b32_e32 v141, 0xffff0000, v175
	v_pk_mul_f32 v[236:237], v[236:237], v[244:245]
	v_pk_mul_f32 v[238:239], v[238:239], v[246:247]
	v_pk_mul_f32 v[240:241], v[240:241], v[248:249]
	v_pk_mul_f32 v[242:243], v[242:243], v[140:141]
	v_pk_mul_f32 v[14:15], v[14:15], v[236:237]
	v_pk_mul_f32 v[16:17], v[16:17], v[238:239]
	v_pk_mul_f32 v[10:11], v[10:11], v[240:241]
	v_pk_mul_f32 v[12:13], v[12:13], v[242:243]
	s_waitcnt vmcnt(2)
	v_lshlrev_b32_e32 v236, 16, v184
	v_and_b32_e32 v237, 0xffff0000, v184
	v_lshlrev_b32_e32 v238, 16, v185
	v_and_b32_e32 v239, 0xffff0000, v185
	v_lshlrev_b32_e32 v240, 16, v186
	v_and_b32_e32 v241, 0xffff0000, v186
	v_lshlrev_b32_e32 v242, 16, v187
	v_and_b32_e32 v243, 0xffff0000, v187
	v_max_f32_e32 v236, 0xda24260, v236
	v_max_f32_e32 v237, 0xda24260, v237
	v_max_f32_e32 v238, 0xda24260, v238
	v_max_f32_e32 v239, 0xda24260, v239
	v_max_f32_e32 v240, 0xda24260, v240
	v_max_f32_e32 v241, 0xda24260, v241
	v_max_f32_e32 v242, 0xda24260, v242
	v_max_f32_e32 v243, 0xda24260, v243
	v_rcp_f32_e32 v236, v236
	v_rcp_f32_e32 v237, v237
	v_rcp_f32_e32 v238, v238
	v_rcp_f32_e32 v239, v239
	v_rcp_f32_e32 v240, v240
	v_rcp_f32_e32 v241, v241
	v_rcp_f32_e32 v242, v242
	v_rcp_f32_e32 v243, v243
	v_lshlrev_b32_e32 v244, 16, v180
	v_and_b32_e32 v245, 0xffff0000, v180
	v_lshlrev_b32_e32 v246, 16, v181
	v_and_b32_e32 v247, 0xffff0000, v181
	v_lshlrev_b32_e32 v248, 16, v182
	v_and_b32_e32 v249, 0xffff0000, v182
	v_lshlrev_b32_e32 v140, 16, v183
	v_and_b32_e32 v141, 0xffff0000, v183
	v_pk_mul_f32 v[236:237], v[236:237], v[244:245]
	v_pk_mul_f32 v[238:239], v[238:239], v[246:247]
	v_pk_mul_f32 v[240:241], v[240:241], v[248:249]
	v_pk_mul_f32 v[242:243], v[242:243], v[140:141]
	v_pk_mul_f32 v[38:39], v[38:39], v[236:237]
	v_pk_mul_f32 v[40:41], v[40:41], v[238:239]
	v_pk_mul_f32 v[34:35], v[34:35], v[240:241]
	v_pk_mul_f32 v[36:37], v[36:37], v[242:243]
	s_waitcnt vmcnt(0)
	v_lshlrev_b32_e32 v236, 16, v192
	v_and_b32_e32 v237, 0xffff0000, v192
	v_lshlrev_b32_e32 v238, 16, v193
	v_and_b32_e32 v239, 0xffff0000, v193
	v_lshlrev_b32_e32 v240, 16, v194
	v_and_b32_e32 v241, 0xffff0000, v194
	v_lshlrev_b32_e32 v242, 16, v195
	v_and_b32_e32 v243, 0xffff0000, v195
	v_max_f32_e32 v236, 0xda24260, v236
	v_max_f32_e32 v237, 0xda24260, v237
	v_max_f32_e32 v238, 0xda24260, v238
	v_max_f32_e32 v239, 0xda24260, v239
	v_max_f32_e32 v240, 0xda24260, v240
	v_max_f32_e32 v241, 0xda24260, v241
	v_max_f32_e32 v242, 0xda24260, v242
	v_max_f32_e32 v243, 0xda24260, v243
	v_rcp_f32_e32 v236, v236
	v_rcp_f32_e32 v237, v237
	v_rcp_f32_e32 v238, v238
	v_rcp_f32_e32 v239, v239
	v_rcp_f32_e32 v240, v240
	v_rcp_f32_e32 v241, v241
	v_rcp_f32_e32 v242, v242
	v_rcp_f32_e32 v243, v243
	v_lshlrev_b32_e32 v244, 16, v188
	v_and_b32_e32 v245, 0xffff0000, v188
	v_lshlrev_b32_e32 v246, 16, v189
	v_and_b32_e32 v247, 0xffff0000, v189
	v_lshlrev_b32_e32 v248, 16, v190
	v_and_b32_e32 v249, 0xffff0000, v190
	v_lshlrev_b32_e32 v140, 16, v191
	v_and_b32_e32 v141, 0xffff0000, v191
	v_pk_mul_f32 v[236:237], v[236:237], v[244:245]
	v_pk_mul_f32 v[238:239], v[238:239], v[246:247]
	v_pk_mul_f32 v[240:241], v[240:241], v[248:249]
	v_pk_mul_f32 v[242:243], v[242:243], v[140:141]
	v_pk_mul_f32 v[6:7], v[6:7], v[236:237]
	v_pk_mul_f32 v[8:9], v[8:9], v[238:239]
	v_pk_mul_f32 v[2:3], v[2:3], v[240:241]
	v_pk_mul_f32 v[4:5], v[4:5], v[242:243]
	s_branch .Lmg_done
.Lmg_fin:
	v_add_u32_e32 v142, 0x5a00, v142
	global_load_dwordx4 v[164:167], v142, s[34:35]
	global_load_dwordx4 v[168:171], v142, s[34:35] offset:256
	v_add_u32_e32 v142, 0x6a000, v142
	global_load_dwordx4 v[172:175], v142, s[34:35]
	global_load_dwordx4 v[176:179], v142, s[34:35] offset:256
	v_add_u32_e32 v142, 0x6a000, v142
	global_load_dwordx4 v[180:183], v142, s[34:35]
	global_load_dwordx4 v[184:187], v142, s[34:35] offset:256
	v_add_u32_e32 v142, 0x6a000, v142
	global_load_dwordx4 v[188:191], v142, s[34:35]
	global_load_dwordx4 v[192:195], v142, s[34:35] offset:256
	v_add_u32_e32 v142, 0x212000, v142
	global_load_dwordx4 v[196:199], v142, s[34:35]
	global_load_dwordx4 v[224:227], v142, s[34:35] offset:256
	v_add_u32_e32 v142, 0x6a000, v142
	s_waitcnt vmcnt(9)
	v_lshlrev_b32_e32 v244, 16, v164
	v_and_b32_e32 v245, 0xffff0000, v164
	v_lshlrev_b32_e32 v246, 16, v165
	v_and_b32_e32 v247, 0xffff0000, v165
	v_lshlrev_b32_e32 v248, 16, v166
	v_and_b32_e32 v249, 0xffff0000, v166
	v_lshlrev_b32_e32 v140, 16, v167
	v_and_b32_e32 v141, 0xffff0000, v167
	v_mul_f32_e32 v126, v126, v244
	v_mul_f32_e32 v127, v127, v245
	v_mul_f32_e32 v128, v128, v246
	v_mul_f32_e32 v129, v129, v247
	v_mul_f32_e32 v122, v122, v248
	v_mul_f32_e32 v123, v123, v249
	v_mul_f32_e32 v124, v124, v140
	v_mul_f32_e32 v125, v125, v141
	v_cvt_pk_bf16_f32 v164, v126, v127
	v_cvt_pk_bf16_f32 v165, v128, v129
	v_cvt_pk_bf16_f32 v166, v122, v123
	v_cvt_pk_bf16_f32 v167, v124, v125
	global_store_dwordx4 v143, v[164:167], s[16:17]
	s_nop 0
	global_load_dwordx4 v[164:167], v142, s[34:35]
	s_waitcnt vmcnt(10)
	v_lshlrev_b32_e32 v244, 16, v168
	v_and_b32_e32 v245, 0xffff0000, v168
	v_lshlrev_b32_e32 v246, 16, v169
	v_and_b32_e32 v247, 0xffff0000, v169
	v_lshlrev_b32_e32 v248, 16, v170
	v_and_b32_e32 v249, 0xffff0000, v170
	v_lshlrev_b32_e32 v140, 16, v171
	v_and_b32_e32 v141, 0xffff0000, v171
	v_mul_f32_e32 v94, v94, v244
	v_mul_f32_e32 v95, v95, v245
	v_mul_f32_e32 v96, v96, v246
	v_mul_f32_e32 v97, v97, v247
	v_mul_f32_e32 v90, v90, v248
	v_mul_f32_e32 v91, v91, v249
	v_mul_f32_e32 v92, v92, v140
	v_mul_f32_e32 v93, v93, v141
	v_cvt_pk_bf16_f32 v168, v94, v95
	v_cvt_pk_bf16_f32 v169, v96, v97
	v_cvt_pk_bf16_f32 v170, v90, v91
	v_cvt_pk_bf16_f32 v171, v92, v93
	global_store_dwordx4 v143, v[168:171], s[16:17] offset:256
	v_add_u32_e32 v143, 0x10000, v143
	global_load_dwordx4 v[168:171], v142, s[34:35] offset:256
	v_add_u32_e32 v142, 0x6a000, v142
	s_waitcnt vmcnt(11)
	v_lshlrev_b32_e32 v244, 16, v172
	v_and_b32_e32 v245, 0xffff0000, v172
	v_lshlrev_b32_e32 v246, 16, v173
	v_and_b32_e32 v247, 0xffff0000, v173
	v_lshlrev_b32_e32 v248, 16, v174
	v_and_b32_e32 v249, 0xffff0000, v174
	v_lshlrev_b32_e32 v140, 16, v175
	v_and_b32_e32 v141, 0xffff0000, v175
	v_mul_f32_e32 v118, v118, v244
	v_mul_f32_e32 v119, v119, v245
	v_mul_f32_e32 v120, v120, v246
	v_mul_f32_e32 v121, v121, v247
	v_mul_f32_e32 v114, v114, v248
	v_mul_f32_e32 v115, v115, v249
	v_mul_f32_e32 v116, v116, v140
	v_mul_f32_e32 v117, v117, v141
	v_cvt_pk_bf16_f32 v172, v118, v119
	v_cvt_pk_bf16_f32 v173, v120, v121
	v_cvt_pk_bf16_f32 v174, v114, v115
	v_cvt_pk_bf16_f32 v175, v116, v117
	global_store_dwordx4 v143, v[172:175], s[16:17]
	s_nop 0
	global_load_dwordx4 v[172:175], v142, s[34:35]
	s_waitcnt vmcnt(12)
	v_lshlrev_b32_e32 v244, 16, v176
	v_and_b32_e32 v245, 0xffff0000, v176
	v_lshlrev_b32_e32 v246, 16, v177
	v_and_b32_e32 v247, 0xffff0000, v177
	v_lshlrev_b32_e32 v248, 16, v178
	v_and_b32_e32 v249, 0xffff0000, v178
	v_lshlrev_b32_e32 v140, 16, v179
	v_and_b32_e32 v141, 0xffff0000, v179
	v_mul_f32_e32 v86, v86, v244
	v_mul_f32_e32 v87, v87, v245
	v_mul_f32_e32 v88, v88, v246
	v_mul_f32_e32 v89, v89, v247
	v_mul_f32_e32 v82, v82, v248
	v_mul_f32_e32 v83, v83, v249
	v_mul_f32_e32 v84, v84, v140
	v_mul_f32_e32 v85, v85, v141
	v_cvt_pk_bf16_f32 v176, v86, v87
	v_cvt_pk_bf16_f32 v177, v88, v89
	v_cvt_pk_bf16_f32 v178, v82, v83
	v_cvt_pk_bf16_f32 v179, v84, v85
	global_store_dwordx4 v143, v[176:179], s[16:17] offset:256
	v_add_u32_e32 v143, 0x10000, v143
	global_load_dwordx4 v[176:179], v142, s[34:35] offset:256
	v_add_u32_e32 v142, 0x6a000, v142
	s_waitcnt vmcnt(13)
	v_lshlrev_b32_e32 v244, 16, v180
	v_and_b32_e32 v245, 0xffff0000, v180
	v_lshlrev_b32_e32 v246, 16, v181
	v_and_b32_e32 v247, 0xffff0000, v181
	v_lshlrev_b32_e32 v248, 16, v182
	v_and_b32_e32 v249, 0xffff0000, v182
	v_lshlrev_b32_e32 v140, 16, v183
	v_and_b32_e32 v141, 0xffff0000, v183
	v_mul_f32_e32 v110, v110, v244
	v_mul_f32_e32 v111, v111, v245
	v_mul_f32_e32 v112, v112, v246
	v_mul_f32_e32 v113, v113, v247
	v_mul_f32_e32 v106, v106, v248
	v_mul_f32_e32 v107, v107, v249
	v_mul_f32_e32 v108, v108, v140
	v_mul_f32_e32 v109, v109, v141
	v_cvt_pk_bf16_f32 v180, v110, v111
	v_cvt_pk_bf16_f32 v181, v112, v113
	v_cvt_pk_bf16_f32 v182, v106, v107
	v_cvt_pk_bf16_f32 v183, v108, v109
	global_store_dwordx4 v143, v[180:183], s[16:17]
	s_nop 0
	global_load_dwordx4 v[180:183], v142, s[34:35]
	s_waitcnt vmcnt(14)
	v_lshlrev_b32_e32 v244, 16, v184
	v_and_b32_e32 v245, 0xffff0000, v184
	v_lshlrev_b32_e32 v246, 16, v185
	v_and_b32_e32 v247, 0xffff0000, v185
	v_lshlrev_b32_e32 v248, 16, v186
	v_and_b32_e32 v249, 0xffff0000, v186
	v_lshlrev_b32_e32 v140, 16, v187
	v_and_b32_e32 v141, 0xffff0000, v187
	v_mul_f32_e32 v78, v78, v244
	v_mul_f32_e32 v79, v79, v245
	v_mul_f32_e32 v80, v80, v246
	v_mul_f32_e32 v81, v81, v247
	v_mul_f32_e32 v74, v74, v248
	v_mul_f32_e32 v75, v75, v249
	v_mul_f32_e32 v76, v76, v140
	v_mul_f32_e32 v77, v77, v141
	v_cvt_pk_bf16_f32 v184, v78, v79
	v_cvt_pk_bf16_f32 v185, v80, v81
	v_cvt_pk_bf16_f32 v186, v74, v75
	v_cvt_pk_bf16_f32 v187, v76, v77
	global_store_dwordx4 v143, v[184:187], s[16:17] offset:256
	v_add_u32_e32 v143, 0x10000, v143
	global_load_dwordx4 v[184:187], v142, s[34:35] offset:256
	s_waitcnt vmcnt(15)
	v_lshlrev_b32_e32 v244, 16, v188
	v_and_b32_e32 v245, 0xffff0000, v188
	v_lshlrev_b32_e32 v246, 16, v189
	v_and_b32_e32 v247, 0xffff0000, v189
	v_lshlrev_b32_e32 v248, 16, v190
	v_and_b32_e32 v249, 0xffff0000, v190
	v_lshlrev_b32_e32 v140, 16, v191
	v_and_b32_e32 v141, 0xffff0000, v191
	v_mul_f32_e32 v102, v102, v244
	v_mul_f32_e32 v103, v103, v245
	v_mul_f32_e32 v104, v104, v246
	v_mul_f32_e32 v105, v105, v247
	v_mul_f32_e32 v98, v98, v248
	v_mul_f32_e32 v99, v99, v249
	v_mul_f32_e32 v100, v100, v140
	v_mul_f32_e32 v101, v101, v141
	v_cvt_pk_bf16_f32 v188, v102, v103
	v_cvt_pk_bf16_f32 v189, v104, v105
	v_cvt_pk_bf16_f32 v190, v98, v99
	v_cvt_pk_bf16_f32 v191, v100, v101
	global_store_dwordx4 v143, v[188:191], s[16:17]
	s_nop 0
	s_waitcnt vmcnt(15)
	v_lshlrev_b32_e32 v244, 16, v192
	v_and_b32_e32 v245, 0xffff0000, v192
	v_lshlrev_b32_e32 v246, 16, v193
	v_and_b32_e32 v247, 0xffff0000, v193
	v_lshlrev_b32_e32 v248, 16, v194
	v_and_b32_e32 v249, 0xffff0000, v194
	v_lshlrev_b32_e32 v140, 16, v195
	v_and_b32_e32 v141, 0xffff0000, v195
	v_mul_f32_e32 v70, v70, v244
	v_mul_f32_e32 v71, v71, v245
	v_mul_f32_e32 v72, v72, v246
	v_mul_f32_e32 v73, v73, v247
	v_mul_f32_e32 v66, v66, v248
	v_mul_f32_e32 v67, v67, v249
	v_mul_f32_e32 v68, v68, v140
	v_mul_f32_e32 v69, v69, v141
	v_cvt_pk_bf16_f32 v192, v70, v71
	v_cvt_pk_bf16_f32 v193, v72, v73
	v_cvt_pk_bf16_f32 v194, v66, v67
	v_cvt_pk_bf16_f32 v195, v68, v69
	global_store_dwordx4 v143, v[192:195], s[16:17] offset:256
	v_add_u32_e32 v143, 0x50000, v143
	s_waitcnt vmcnt(15)
	v_lshlrev_b32_e32 v244, 16, v196
	v_and_b32_e32 v245, 0xffff0000, v196
	v_lshlrev_b32_e32 v246, 16, v197
	v_and_b32_e32 v247, 0xffff0000, v197
	v_lshlrev_b32_e32 v248, 16, v198
	v_and_b32_e32 v249, 0xffff0000, v198
	v_lshlrev_b32_e32 v140, 16, v199
	v_and_b32_e32 v141, 0xffff0000, v199
	v_mul_f32_e32 v62, v62, v244
	v_mul_f32_e32 v63, v63, v245
	v_mul_f32_e32 v64, v64, v246
	v_mul_f32_e32 v65, v65, v247
	v_mul_f32_e32 v58, v58, v248
	v_mul_f32_e32 v59, v59, v249
	v_mul_f32_e32 v60, v60, v140
	v_mul_f32_e32 v61, v61, v141
	v_cvt_pk_bf16_f32 v196, v62, v63
	v_cvt_pk_bf16_f32 v197, v64, v65
	v_cvt_pk_bf16_f32 v198, v58, v59
	v_cvt_pk_bf16_f32 v199, v60, v61
	global_store_dwordx4 v143, v[196:199], s[16:17]
	s_nop 0
	s_waitcnt vmcnt(15)
	v_lshlrev_b32_e32 v244, 16, v224
	v_and_b32_e32 v245, 0xffff0000, v224
	v_lshlrev_b32_e32 v246, 16, v225
	v_and_b32_e32 v247, 0xffff0000, v225
	v_lshlrev_b32_e32 v248, 16, v226
	v_and_b32_e32 v249, 0xffff0000, v226
	v_lshlrev_b32_e32 v140, 16, v227
	v_and_b32_e32 v141, 0xffff0000, v227
	v_mul_f32_e32 v30, v30, v244
	v_mul_f32_e32 v31, v31, v245
	v_mul_f32_e32 v32, v32, v246
	v_mul_f32_e32 v33, v33, v247
	v_mul_f32_e32 v26, v26, v248
	v_mul_f32_e32 v27, v27, v249
	v_mul_f32_e32 v28, v28, v140
	v_mul_f32_e32 v29, v29, v141
	v_cvt_pk_bf16_f32 v224, v30, v31
	v_cvt_pk_bf16_f32 v225, v32, v33
	v_cvt_pk_bf16_f32 v226, v26, v27
	v_cvt_pk_bf16_f32 v227, v28, v29
	global_store_dwordx4 v143, v[224:227], s[16:17] offset:256
	v_add_u32_e32 v143, 0x10000, v143
	s_waitcnt vmcnt(14)
	v_lshlrev_b32_e32 v244, 16, v164
	v_and_b32_e32 v245, 0xffff0000, v164
	v_lshlrev_b32_e32 v246, 16, v165
	v_and_b32_e32 v247, 0xffff0000, v165
	v_lshlrev_b32_e32 v248, 16, v166
	v_and_b32_e32 v249, 0xffff0000, v166
	v_lshlrev_b32_e32 v140, 16, v167
	v_and_b32_e32 v141, 0xffff0000, v167
	v_mul_f32_e32 v54, v54, v244
	v_mul_f32_e32 v55, v55, v245
	v_mul_f32_e32 v56, v56, v246
	v_mul_f32_e32 v57, v57, v247
	v_mul_f32_e32 v50, v50, v248
	v_mul_f32_e32 v51, v51, v249
	v_mul_f32_e32 v52, v52, v140
	v_mul_f32_e32 v53, v53, v141
	v_cvt_pk_bf16_f32 v164, v54, v55
	v_cvt_pk_bf16_f32 v165, v56, v57
	v_cvt_pk_bf16_f32 v166, v50, v51
	v_cvt_pk_bf16_f32 v167, v52, v53
	global_store_dwordx4 v143, v[164:167], s[16:17]
	s_nop 0
	s_waitcnt vmcnt(13)
	v_lshlrev_b32_e32 v244, 16, v168
	v_and_b32_e32 v245, 0xffff0000, v168
	v_lshlrev_b32_e32 v246, 16, v169
	v_and_b32_e32 v247, 0xffff0000, v169
	v_lshlrev_b32_e32 v248, 16, v170
	v_and_b32_e32 v249, 0xffff0000, v170
	v_lshlrev_b32_e32 v140, 16, v171
	v_and_b32_e32 v141, 0xffff0000, v171
	v_mul_f32_e32 v22, v22, v244
	v_mul_f32_e32 v23, v23, v245
	v_mul_f32_e32 v24, v24, v246
	v_mul_f32_e32 v25, v25, v247
	v_mul_f32_e32 v18, v18, v248
	v_mul_f32_e32 v19, v19, v249
	v_mul_f32_e32 v20, v20, v140
	v_mul_f32_e32 v21, v21, v141
	v_cvt_pk_bf16_f32 v168, v22, v23
	v_cvt_pk_bf16_f32 v169, v24, v25
	v_cvt_pk_bf16_f32 v170, v18, v19
	v_cvt_pk_bf16_f32 v171, v20, v21
	global_store_dwordx4 v143, v[168:171], s[16:17] offset:256
	v_add_u32_e32 v143, 0x10000, v143
	s_waitcnt vmcnt(12)
	v_lshlrev_b32_e32 v244, 16, v172
	v_and_b32_e32 v245, 0xffff0000, v172
	v_lshlrev_b32_e32 v246, 16, v173
	v_and_b32_e32 v247, 0xffff0000, v173
	v_lshlrev_b32_e32 v248, 16, v174
	v_and_b32_e32 v249, 0xffff0000, v174
	v_lshlrev_b32_e32 v140, 16, v175
	v_and_b32_e32 v141, 0xffff0000, v175
	v_mul_f32_e32 v46, v46, v244
	v_mul_f32_e32 v47, v47, v245
	v_mul_f32_e32 v48, v48, v246
	v_mul_f32_e32 v49, v49, v247
	v_mul_f32_e32 v42, v42, v248
	v_mul_f32_e32 v43, v43, v249
	v_mul_f32_e32 v44, v44, v140
	v_mul_f32_e32 v45, v45, v141
	v_cvt_pk_bf16_f32 v172, v46, v47
	v_cvt_pk_bf16_f32 v173, v48, v49
	v_cvt_pk_bf16_f32 v174, v42, v43
	v_cvt_pk_bf16_f32 v175, v44, v45
	global_store_dwordx4 v143, v[172:175], s[16:17]
	s_nop 0
	s_waitcnt vmcnt(11)
	v_lshlrev_b32_e32 v244, 16, v176
	v_and_b32_e32 v245, 0xffff0000, v176
	v_lshlrev_b32_e32 v246, 16, v177
	v_and_b32_e32 v247, 0xffff0000, v177
	v_lshlrev_b32_e32 v248, 16, v178
	v_and_b32_e32 v249, 0xffff0000, v178
	v_lshlrev_b32_e32 v140, 16, v179
	v_and_b32_e32 v141, 0xffff0000, v179
	v_mul_f32_e32 v14, v14, v244
	v_mul_f32_e32 v15, v15, v245
	v_mul_f32_e32 v16, v16, v246
	v_mul_f32_e32 v17, v17, v247
	v_mul_f32_e32 v10, v10, v248
	v_mul_f32_e32 v11, v11, v249
	v_mul_f32_e32 v12, v12, v140
	v_mul_f32_e32 v13, v13, v141
	v_cvt_pk_bf16_f32 v176, v14, v15
	v_cvt_pk_bf16_f32 v177, v16, v17
	v_cvt_pk_bf16_f32 v178, v10, v11
	v_cvt_pk_bf16_f32 v179, v12, v13
	global_store_dwordx4 v143, v[176:179], s[16:17] offset:256
	v_add_u32_e32 v143, 0x10000, v143
	s_waitcnt vmcnt(10)
	v_lshlrev_b32_e32 v244, 16, v180
	v_and_b32_e32 v245, 0xffff0000, v180
	v_lshlrev_b32_e32 v246, 16, v181
	v_and_b32_e32 v247, 0xffff0000, v181
	v_lshlrev_b32_e32 v248, 16, v182
	v_and_b32_e32 v249, 0xffff0000, v182
	v_lshlrev_b32_e32 v140, 16, v183
	v_and_b32_e32 v141, 0xffff0000, v183
	v_mul_f32_e32 v38, v38, v244
	v_mul_f32_e32 v39, v39, v245
	v_mul_f32_e32 v40, v40, v246
	v_mul_f32_e32 v41, v41, v247
	v_mul_f32_e32 v34, v34, v248
	v_mul_f32_e32 v35, v35, v249
	v_mul_f32_e32 v36, v36, v140
	v_mul_f32_e32 v37, v37, v141
	v_cvt_pk_bf16_f32 v180, v38, v39
	v_cvt_pk_bf16_f32 v181, v40, v41
	v_cvt_pk_bf16_f32 v182, v34, v35
	v_cvt_pk_bf16_f32 v183, v36, v37
	global_store_dwordx4 v143, v[180:183], s[16:17]
	s_nop 0
	s_waitcnt vmcnt(9)
	v_lshlrev_b32_e32 v244, 16, v184
	v_and_b32_e32 v245, 0xffff0000, v184
	v_lshlrev_b32_e32 v246, 16, v185
	v_and_b32_e32 v247, 0xffff0000, v185
	v_lshlrev_b32_e32 v248, 16, v186
	v_and_b32_e32 v249, 0xffff0000, v186
	v_lshlrev_b32_e32 v140, 16, v187
	v_and_b32_e32 v141, 0xffff0000, v187
	v_mul_f32_e32 v6, v6, v244
	v_mul_f32_e32 v7, v7, v245
	v_mul_f32_e32 v8, v8, v246
	v_mul_f32_e32 v9, v9, v247
	v_mul_f32_e32 v2, v2, v248
	v_mul_f32_e32 v3, v3, v249
	v_mul_f32_e32 v4, v4, v140
	v_mul_f32_e32 v5, v5, v141
	v_cvt_pk_bf16_f32 v184, v6, v7
	v_cvt_pk_bf16_f32 v185, v8, v9
	v_cvt_pk_bf16_f32 v186, v2, v3
	v_cvt_pk_bf16_f32 v187, v4, v5
	global_store_dwordx4 v143, v[184:187], s[16:17] offset:256
	s_nop 0
.Lmg_done:
	s_andn2_b64 vcc, exec, s[40:41]
	s_mov_b64 s[2:3], -1
	s_cbranch_vccnz .LBB0_914
.LBB0_990:
	s_cmp_lg_u32 s47, 2
	s_cbranch_scc1 .LBB0_992
	v_mov_b32_e32 v2, 0
	v_mov_b32_e32 v3, v2
	v_mov_b32_e32 v4, v2
	v_mov_b32_e32 v5, v2
	v_mov_b32_e32 v6, v2
	v_mov_b32_e32 v7, v2
	v_mov_b32_e32 v8, v2
	v_mov_b32_e32 v9, v2
	v_mov_b32_e32 v10, v2
	v_mov_b32_e32 v11, v2
	v_mov_b32_e32 v12, v2
	v_mov_b32_e32 v13, v2
	v_mov_b32_e32 v14, v2
	v_mov_b32_e32 v15, v2
	v_mov_b32_e32 v16, v2
	v_mov_b32_e32 v17, v2
	v_mov_b32_e32 v18, v2
	v_mov_b32_e32 v19, v2
	v_mov_b32_e32 v20, v2
	v_mov_b32_e32 v21, v2
	v_mov_b32_e32 v22, v2
	v_mov_b32_e32 v23, v2
	v_mov_b32_e32 v24, v2
	v_mov_b32_e32 v25, v2
	v_mov_b32_e32 v26, v2
	v_mov_b32_e32 v27, v2
	v_mov_b32_e32 v28, v2
	v_mov_b32_e32 v29, v2
	v_mov_b32_e32 v30, v2
	v_mov_b32_e32 v31, v2
	v_mov_b32_e32 v32, v2
	v_mov_b32_e32 v33, v2
	v_mov_b32_e32 v34, v2
	v_mov_b32_e32 v35, v2
	v_mov_b32_e32 v36, v2
	v_mov_b32_e32 v37, v2
	v_mov_b32_e32 v38, v2
	v_mov_b32_e32 v39, v2
	v_mov_b32_e32 v40, v2
	v_mov_b32_e32 v41, v2
	v_mov_b32_e32 v42, v2
	v_mov_b32_e32 v43, v2
	v_mov_b32_e32 v44, v2
	v_mov_b32_e32 v45, v2
	v_mov_b32_e32 v46, v2
	v_mov_b32_e32 v47, v2
	v_mov_b32_e32 v48, v2
	v_mov_b32_e32 v49, v2
	v_mov_b32_e32 v50, v2
	v_mov_b32_e32 v51, v2
	v_mov_b32_e32 v52, v2
	v_mov_b32_e32 v53, v2
	v_mov_b32_e32 v54, v2
	v_mov_b32_e32 v55, v2
	v_mov_b32_e32 v56, v2
	v_mov_b32_e32 v57, v2
	v_mov_b32_e32 v58, v2
	v_mov_b32_e32 v59, v2
	v_mov_b32_e32 v60, v2
	v_mov_b32_e32 v61, v2
	v_mov_b32_e32 v62, v2
	v_mov_b32_e32 v63, v2
	v_mov_b32_e32 v64, v2
	v_mov_b32_e32 v65, v2
	v_mov_b32_e32 v66, v2
	v_mov_b32_e32 v67, v2
	v_mov_b32_e32 v68, v2
	v_mov_b32_e32 v69, v2
	v_mov_b32_e32 v70, v2
	v_mov_b32_e32 v71, v2
	v_mov_b32_e32 v72, v2
	v_mov_b32_e32 v73, v2
	v_mov_b32_e32 v74, v2
	v_mov_b32_e32 v75, v2
	v_mov_b32_e32 v76, v2
	v_mov_b32_e32 v77, v2
	v_mov_b32_e32 v78, v2
	v_mov_b32_e32 v79, v2
	v_mov_b32_e32 v80, v2
	v_mov_b32_e32 v81, v2
	v_mov_b32_e32 v82, v2
	v_mov_b32_e32 v83, v2
	v_mov_b32_e32 v84, v2
	v_mov_b32_e32 v85, v2
	v_mov_b32_e32 v86, v2
	v_mov_b32_e32 v87, v2
	v_mov_b32_e32 v88, v2
	v_mov_b32_e32 v89, v2
	v_mov_b32_e32 v90, v2
	v_mov_b32_e32 v91, v2
	v_mov_b32_e32 v92, v2
	v_mov_b32_e32 v93, v2
	v_mov_b32_e32 v94, v2
	v_mov_b32_e32 v95, v2
	v_mov_b32_e32 v96, v2
	v_mov_b32_e32 v97, v2
	v_mov_b32_e32 v98, v2
	v_mov_b32_e32 v99, v2
	v_mov_b32_e32 v100, v2
	v_mov_b32_e32 v101, v2
	v_mov_b32_e32 v102, v2
	v_mov_b32_e32 v103, v2
	v_mov_b32_e32 v104, v2
	v_mov_b32_e32 v105, v2
	v_mov_b32_e32 v106, v2
	v_mov_b32_e32 v107, v2
	v_mov_b32_e32 v108, v2
	v_mov_b32_e32 v109, v2
	v_mov_b32_e32 v110, v2
	v_mov_b32_e32 v111, v2
	v_mov_b32_e32 v112, v2
	v_mov_b32_e32 v113, v2
	v_mov_b32_e32 v114, v2
	v_mov_b32_e32 v115, v2
	v_mov_b32_e32 v116, v2
	v_mov_b32_e32 v117, v2
	v_mov_b32_e32 v118, v2
	v_mov_b32_e32 v119, v2
	v_mov_b32_e32 v120, v2
	v_mov_b32_e32 v121, v2
	v_mov_b32_e32 v122, v2
	v_mov_b32_e32 v123, v2
	v_mov_b32_e32 v124, v2
	v_mov_b32_e32 v125, v2
	v_mov_b32_e32 v126, v2
	v_mov_b32_e32 v127, v2
	v_mov_b32_e32 v128, v2
	v_mov_b32_e32 v129, v2
